# combined variant plus: residual epilogues (w_out, down) touch all 128 residual lines of the wave before the first residual batch so later batches hit L2
# baseline (speedup 1.0000x reference)
;     __device__ __forceinline__ void operator()(const f32x4 (&acc)[2][2][4][2], const Unit& u, int wr, int wc, int fr, int fq, int) const {
;         const int row0 = u.pm * BM + wr * 64 + fr, col0 = u.pn * BM + wc * 64 + 8 * fq;
;         const float* Xin = (u.pm * BM < split) ? Xin0 : Xin1 - (size_t)split * ldc;
;     ...
; #pragma unroll
;                 for (int mm = 0; mm < 2; ++mm)
; #pragma unroll
;                     for (int bj = 0; bj < 2; ++bj) xr[mm][bj] = *(const u32x4*)(XB + (size_t)(row0 + ai * HALF + (m0 + mm) * 16) * ldc + col0 + bj * 32);
;             }
.LBB0_932:
	s_andn2_b64 vcc, exec, s[38:39]
	s_cbranch_vccnz .LBB0_934
	v_ashrrev_i32_e32 v219, 31, v218
	v_lshl_add_u64 v[66:67], v[216:217], 1, s[52:53]
	v_lshlrev_b64 v[68:69], 12, v[218:219]
	v_lshl_add_u64 v[68:69], v[66:67], 0, v[68:69]
	v_and_b32_e32 v194, 48, v0
	v_lshlrev_b32_e32 v194, 12, v194
	v_mov_b32_e32 v195, 0
	v_lshl_add_u64 v[196:197], v[68:69], 0, v[194:195]
	global_load_dword v198, v[196:197], off
	s_mov_b64 s[100:101], 0x80000
	v_lshl_add_u64 v[196:197], v[196:197], 0, s[100:101]
	global_load_dword v198, v[196:197], off
	global_load_dwordx4 v[86:89], v[68:69], off
	global_load_dwordx4 v[78:81], v[68:69], off offset:64
	v_lshlrev_b64 v[68:69], 12, v[222:223]
	v_lshl_add_u64 v[66:67], v[66:67], 0, v[68:69]
	global_load_dwordx4 v[70:73], v[66:67], off
	s_nop 0
	global_load_dwordx4 v[66:69], v[66:67], off offset:64

; __device__ __forceinline__ unsigned cvt_pk_bf16(float lo, float hi) { unsigned r; asm volatile("v_cvt_pk_bf16_f32 %0, %1, %2" : "=v"(r) : "v"(lo), "v"(hi)); return r; }
;     __device__ __forceinline__ void operator()(const f32x4 (&acc)[2][2][4][2], const Unit& u, int wr, int wc, int fr, int fq, int) const {
;     ...
;                 for (int mm = 0; mm < 2; ++mm) { const size_t ro = (size_t)(row0 + ai * HALF + (m0 + mm) * 16) * ldc + col0;
; #pragma unroll
;                     for (int bj = 0; bj < 2; ++bj) { xf[mm][bj][0] = *(const f32x4*)(Xin + ro + bj * 32); xf[mm][bj][1] = *(const f32x4*)(Xin + ro + bj * 32 + 4); } }
;             } else {
; #pragma unroll
;                 for (int mm = 0; mm < 2; ++mm)
; #pragma unroll
;                     for (int bj = 0; bj < 2; ++bj) xr[mm][bj] = *(const u32x4*)(XB + (size_t)(row0 + ai * HALF + (m0 + mm) * 16) * ldc + col0 + bj * 32);
;             }
;             asm volatile("" ::: "memory");
; #pragma unroll
;             for (int mm = 0; mm < 2; ++mm) { const int m = m0 + mm; const int row = row0 + ai * HALF + m * 16; const size_t ro = (size_t)row * ldc + col0; float ss = 0.f;
; #pragma unroll
;                 for (int bj = 0; bj < 2; ++bj) { f32x4 x0, x1;
;                     if (Xin0) { x0 = xf[mm][bj][0]; x1 = xf[mm][bj][1]; }
;                     else { const u32x4 w = xr[mm][bj];
;                         x0 = (f32x4){__uint_as_float(w.x << 16), __uint_as_float(w.x & 0xffff0000u), __uint_as_float(w.y << 16), __uint_as_float(w.y & 0xffff0000u)};
;                         x1 = (f32x4){__uint_as_float(w.z << 16), __uint_as_float(w.z & 0xffff0000u), __uint_as_float(w.w << 16), __uint_as_float(w.w & 0xffff0000u)}; }
;                     x0 = x0 + acc[ai][bj][m][0]; x1 = x1 + acc[ai][bj][m][1];
;                     if (Xout) { *(f32x4*)(Xout + ro + bj * 32) = x0; *(f32x4*)(Xout + ro + bj * 32 + 4) = x1; }
;                     else { u32x4 w; w.x = cvt_pk_bf16(x0[0], x0[1]); w.y = cvt_pk_bf16(x0[2], x0[3]); w.z = cvt_pk_bf16(x1[0], x1[1]); w.w = cvt_pk_bf16(x1[2], x1[3]); *(u32x4*)(XB + ro + bj * 32) = w;
.LBB0_1074:
	v_lshl_add_u32 v152, s37, 8, v1
	v_lshl_or_b32 v156, s36, 8, v165
	v_ashrrev_i32_e32 v157, 31, v156
	v_ashrrev_i32_e32 v153, 31, v152
	v_lshl_add_u64 v[154:155], v[156:157], 1, s[68:69]
	v_lshlrev_b64 v[130:131], 12, v[152:153]
	v_or_b32_e32 v158, 16, v152
	v_lshl_add_u64 v[130:131], v[154:155], 0, v[130:131]
	v_ashrrev_i32_e32 v159, 31, v158
	v_and_b32_e32 v194, 48, v0
	v_lshlrev_b32_e32 v194, 12, v194
	v_mov_b32_e32 v195, 0
	v_lshl_add_u64 v[196:197], v[130:131], 0, v[194:195]
	global_load_dword v198, v[196:197], off
	s_mov_b64 s[100:101], 0x80000
	v_lshl_add_u64 v[196:197], v[196:197], 0, s[100:101]
	global_load_dword v198, v[196:197], off
	global_load_dwordx4 v[168:171], v[130:131], off
	global_load_dwordx4 v[138:141], v[130:131], off offset:64
	v_lshlrev_b64 v[132:133], 12, v[158:159]
	v_lshl_add_u64 v[130:131], v[154:155], 0, v[132:133]
	global_load_dwordx4 v[134:137], v[130:131], off
	s_nop 0
	global_load_dwordx4 v[130:133], v[130:131], off offset:64
	v_cndmask_b32_e64 v160, 0, 1, s[80:81]
	v_cmp_ne_u32_e64 s[38:39], 1, v160
	v_lshlrev_b64 v[160:161], 11, v[152:153]
	v_lshl_add_u64 v[162:163], v[160:161], 0, v[156:157]
	s_mov_b64 s[46:47], -1
	s_andn2_b64 vcc, exec, s[80:81]
	v_lshl_add_u64 v[162:163], v[162:163], 2, s[62:63]
	s_waitcnt vmcnt(0)
	v_lshlrev_b32_e32 v172, 16, v168
	v_and_b32_e32 v173, 0xffff0000, v168
	v_lshlrev_b32_e32 v168, 16, v169
	v_and_b32_e32 v169, 0xffff0000, v169
	v_lshlrev_b32_e32 v174, 16, v170
	v_and_b32_e32 v175, 0xffff0000, v170
	v_lshlrev_b32_e32 v170, 16, v171
	v_and_b32_e32 v171, 0xffff0000, v171
	v_pk_add_f32 v[128:129], v[128:129], v[168:169]
	v_pk_add_f32 v[126:127], v[126:127], v[172:173]
	v_pk_add_f32 v[124:125], v[124:125], v[170:171]
	v_pk_add_f32 v[122:123], v[122:123], v[174:175]
	s_cbranch_vccnz .LBB0_1076
	s_mov_b64 s[46:47], 0
	global_store_dwordx4 v[162:163], v[126:129], off
	global_store_dwordx4 v[162:163], v[122:125], off offset:16
